# attention LDS-DMA staging v2: K/V row addresses from one u24 multiply per 32-row group (no 64-bit mads), one address set shared by the K (offset 0) and V (offset 2048) DMAs, original LDS layout
# baseline (speedup 1.0000x reference)
; #define LAS __attribute__((address_space(3)))
; __device__ __forceinline__ int mk_lane() { int l; asm volatile("v_mbcnt_lo_u32_b32 %0, -1, 0\n\tv_mbcnt_hi_u32_b32 %0, -1, %0" : "=v"(l)); return l; }
; __device__ __forceinline__ void attn_phase(Frame& F, h16* Obr) {
;     const h16* Hq = (const h16*)(F.ws + WS_R1 + R1_HQKV); float* Lse = (float*)(F.ws + WS_LSE);
;     const int tid_ = F.wave * 64 + mk_lane();
;     LAS unsigned char* lds = F.lds; const int tid = tid_, lane = tid & 63, w = F.wave, q16 = lane & 15, g = lane >> 4;
;     constexpr int NITEM = NSEQ * NH * 48;
;     int i_lo, i_hi, i_st;
;     if (F.G % 8 == 0) { const int per = F.G / 8, x = F.vcu / per, j = F.vcu % per; i_lo = x * (NITEM / 8) + j; i_hi = (x + 1) * (NITEM / 8); i_st = per; }
;     else { i_lo = (int)((long)F.vcu * NITEM / F.G); i_hi = (int)((long)(F.vcu + 1) * NITEM / F.G); i_st = 1; }
;     if (i_lo >= i_hi) return;
;     u32x4 kv[17]; h16x8 qn[4];
;     AttItem nx = att_decode(i_lo);
;     ATT_ISSUE(nx);
.LBB0_709:
	s_cmp_ge_i32 s14, s16
	s_cbranch_scc1 .LBB0_739
	v_readlane_b32 s100, v252, 7
	s_nop 3
	s_lshl_b32 s100, s100, 6
	s_add_u32 s101, s100, 0xf800
	s_mul_hi_i32 s0, s14, 0x2aaaaaab
	s_lshr_b32 s1, s0, 31
	s_ashr_i32 s0, s0, 3
	s_add_i32 s1, s0, s1
	s_mul_i32 s0, s1, 48
	s_sub_i32 s2, s14, s0
	s_cmp_lt_i32 s2, 16
	s_cbranch_scc1 .LBB0_715
	s_cmp_gt_u32 s2, 31
	s_mov_b64 s[22:23], -1
	s_cbranch_scc0 .LBB0_713
	s_sub_i32 s49, s2, 32
	s_mov_b64 s[22:23], 0

.LBB0_719:
	v_readlane_b32 s4, v254, 42
	s_and_b32 s22, s1, 7
	s_lshl_b32 s51, s2, 7
	v_add_u32_e32 v73, s4, v70
	s_ashr_i32 s4, s1, 3
	s_ashr_i32 s5, s4, 31
	s_ff1_i32_b32 s1, s0
	s_lshl_b64 s[28:29], s[4:5], 11
	s_lshr_b32 s50, 0x800, s1
	v_ashrrev_i32_e32 v156, 4, v73
	s_lshl_b32 s1, s22, 7
	s_lshl_b32 s2, s22, 8
	v_readlane_b32 s4, v252, 3
	v_readlane_b32 s5, v252, 4
	s_add_u32 s4, s4, s2
	v_subrev_u32_e32 v157, 64, v156
	s_addc_u32 s5, s5, 0
	v_add_u32_e32 v72, s51, v157
	s_add_i32 s2, s50, -1
	v_and_b32_e32 v71, 15, v70
	s_add_u32 s26, s28, s49
	s_addc_u32 s27, s29, 0
	s_movk_i32 s40, 0x100
	v_cmp_gt_i32_e64 s[36:37], s40, v73
	v_lshlrev_b32_e32 v210, 2, v156
	v_and_b32_e32 v210, 12, v210
	v_bfe_u32 v211, v156, 2, 2
	v_or_b32_e32 v210, v210, v211
	v_xor_b32_e32 v210, v71, v210
	v_lshlrev_b32_e32 v210, 4, v210
	v_mov_b32_e32 v211, 0
	s_mul_i32 s40, s26, 0x1800
	s_add_u32 s40, s40, 0x800
	v_add_u32_e32 v210, s40, v210
	v_lshl_add_u64 v[68:69], s[4:5], 0, v[210:211]
	s_mul_i32 s41, s0, 0x1800
	v_mov_b32_e32 v1, 0
	v_mov_b32_e32 v9, 0
	v_mov_b32_e32 v21, 0
	v_mov_b32_e32 v29, 0
	v_med3_i32 v0, v72, 0, s2
	v_mul_u32_u24_e32 v0, s41, v0
	v_lshl_add_u64 v[36:37], v[0:1], 0, v[68:69]
	s_add_u32 m0, s100, 0x0
	s_nop 0
	global_load_lds_dwordx4 v[36:37], off
	v_add_u32_e32 v8, 0x20, v72
	v_med3_i32 v8, v8, 0, s2
	v_mul_u32_u24_e32 v8, s41, v8
	v_lshl_add_u64 v[38:39], v[8:9], 0, v[68:69]
	s_add_u32 m0, s100, 0x2000
	s_nop 0
	global_load_lds_dwordx4 v[38:39], off
	v_add_u32_e32 v20, 0x40, v72
	v_med3_i32 v20, v20, 0, s2
	v_mul_u32_u24_e32 v20, s41, v20
	v_lshl_add_u64 v[44:45], v[20:21], 0, v[68:69]
	s_add_u32 m0, s100, 0x4000
	s_nop 0
	global_load_lds_dwordx4 v[44:45], off
	v_add_u32_e32 v28, 0x60, v72
	v_med3_i32 v28, v28, 0, s2
	v_mul_u32_u24_e32 v28, s41, v28
	v_lshl_add_u64 v[46:47], v[28:29], 0, v[68:69]
	s_add_u32 m0, s100, 0x6000
	s_nop 0
	global_load_lds_dwordx4 v[46:47], off
	v_add_u32_e32 v0, 0x80, v72
	v_med3_i32 v0, v0, 0, s2
	v_mul_u32_u24_e32 v0, s41, v0
	v_lshl_add_u64 v[52:53], v[0:1], 0, v[68:69]
	s_add_u32 m0, s100, 0x8000
	s_nop 0
	global_load_lds_dwordx4 v[52:53], off
	v_add_u32_e32 v8, 0xa0, v72
	v_med3_i32 v8, v8, 0, s2
	v_mul_u32_u24_e32 v8, s41, v8
	v_lshl_add_u64 v[54:55], v[8:9], 0, v[68:69]
	s_add_u32 m0, s100, 0xa000
	s_nop 0
	global_load_lds_dwordx4 v[54:55], off
	v_add_u32_e32 v20, 0xc0, v72
	v_med3_i32 v20, v20, 0, s2
	v_mul_u32_u24_e32 v20, s41, v20
	v_lshl_add_u64 v[60:61], v[20:21], 0, v[68:69]
	s_add_u32 m0, s100, 0xc000
	s_nop 0
	global_load_lds_dwordx4 v[60:61], off
	v_add_u32_e32 v28, 0xe0, v72
	v_med3_i32 v28, v28, 0, s2
	v_mul_u32_u24_e32 v28, s41, v28
	v_lshl_add_u64 v[62:63], v[28:29], 0, v[68:69]
	s_add_u32 m0, s100, 0xe000
	s_nop 0
	global_load_lds_dwordx4 v[62:63], off
	v_add_u32_e32 v0, 0x100, v72
	v_med3_i32 v0, v0, 0, s2
	v_mul_u32_u24_e32 v0, s41, v0
	v_lshl_add_u64 v[16:17], v[0:1], 0, v[68:69]
; __device__ __forceinline__ void attn_phase(Frame& F, h16* Obr) {
;     ...
;         const int idx0 = cu.idx0, L = cu.L;
;         const int qtok = cu.p + cu.r * (idx0 + 16 * w + q16);
;         f32x4 sc[9];
;         h16x8 kfb[2][4];
; #pragma unroll
;         for (int s = 0; s < 4; ++s) kfb[0][s] = *(const LAS h16x8*)(lds + ATT_K + att_off(16 * w + q16, 4 * s + g));
; #pragma unroll
;         for (int tt = 0; tt < 9; ++tt) {
;             if (tt + 1 < 9) {
; #pragma unroll
;                 for (int s = 0; s < 4; ++s) kfb[(tt + 1) & 1][s] = *(const LAS h16x8*)(lds + ATT_K + att_off(16 * (w + tt + 1) + q16, 4 * s + g)); }
;             asm volatile("" ::: "memory");
;             f32x4 a = {0.f, 0.f, 0.f, 0.f};
; #pragma unroll
;             for (int s = 0; s < 4; ++s) a = __builtin_amdgcn_mfma_f32_16x16x32_f16(kfb[tt & 1][s], Qf[s], a, 0, 0, 0);
;             sc[tt] = a; }
;         const int ql = 16 * w + q16;
;         const int clo = ql > 64 - idx0 ? ql : 64 - idx0, chi = (ql + 128) < (L + 63 - idx0) ? (ql + 128) : (L + 63 - idx0);
;         const unsigned span = (unsigned)(chi - clo); const int cb = 16 * w + 4 * g - clo;
;         float mx = -3.0e38f;
; #pragma unroll
;         for (int tt = 0; tt < 9; ++tt)
; #pragma unroll
;             for (int e = 0; e < 4; ++e) { const bool ok = (unsigned)(cb + 16 * tt + e) <= span; sc[tt][e] = ok ? sc[tt][e] : -3.0e38f; mx = fmaxf(mx, sc[tt][e]); }
;         mx = fmaxf(mx, shx<16>(mx)); mx = fmaxf(mx, shx<32>(mx));
;         float den = 0.f;
; #pragma unroll
;         for (int tt = 0; tt < 9; ++tt)
; #pragma unroll
;             for (int e = 0; e < 4; ++e) { const float pv = __builtin_amdgcn_exp2f(sc[tt][e] - mx); sc[tt][e] = pv; den += pv; }
;         den += shx<16>(den); den += shx<32>(den);
;         h16x8 Pf[5];
; #pragma unroll
;         for (int ks = 0; ks < 5; ++ks) { u32x4 wv; wv.x = pk_h2(sc[2 * ks][0], sc[2 * ks][1]); wv.y = pk_h2(sc[2 * ks][2], sc[2 * ks][3]);
;             if (ks < 4) { wv.z = pk_h2(sc[2 * ks + 1][0], sc[2 * ks + 1][1]); wv.w = pk_h2(sc[2 * ks + 1][2], sc[2 * ks + 1][3]); } else { wv.z = 0u; wv.w = 0u; }
;             Pf[ks] = __builtin_bit_cast(h16x8, wv); }
;         const float rden = 1.0f / den;
;         unsigned char* op = (unsigned char*)Obr + ((size_t)cu.br * M + cu.rowb + qtok) * 1024 + cu.h * 128 + 4 * g;
;         const float rs16 = rden * 16.0f;
.LBB0_721:
	s_or_b64 exec, exec, s[38:39]
	v_readlane_b32 s6, v252, 7
	v_lshlrev_b32_e32 v69, 3, v71
	s_add_i32 s2, s51, s6
	v_lshlrev_b32_e32 v208, 1, v69
	v_or_b32_e32 v69, s2, v71
	v_mul_lo_u32 v69, v69, s0
	v_readlane_b32 s4, v252, 3
	v_add_u32_e32 v72, s49, v69
	v_readlane_b32 s5, v252, 4
	v_ashrrev_i32_e32 v73, 31, v72
	v_lshl_add_u64 v[72:73], s[28:29], 0, v[72:73]
	v_mov_b64_e32 v[74:75], s[4:5]
	v_lshlrev_b32_e32 v210, 2, v156
	v_and_b32_e32 v210, 12, v210
	v_bfe_u32 v211, v156, 2, 2
	v_or_b32_e32 v210, v210, v211
	v_xor_b32_e32 v210, v71, v210
	v_lshlrev_b32_e32 v210, 4, v210
	v_mov_b32_e32 v211, 0
	v_lshl_add_u64 v[148:149], s[4:5], 0, v[210:211]
	v_mad_u64_u32 v[74:75], s[4:5], v72, s35, v[74:75]
	v_bfe_u32 v76, v70, 4, 2
	v_mad_i32_i24 v75, v73, s35, v75
	s_lshl_b32 s2, s1, 1
	v_lshl_add_u64 v[72:73], v[74:75], 0, s[2:3]
	v_lshlrev_b32_e32 v208, 4, v76
	v_lshl_add_u64 v[72:73], v[72:73], 0, v[208:209]
	global_load_dwordx4 v[84:87], v[72:73], off offset:192
	global_load_dwordx4 v[88:91], v[72:73], off offset:128
	global_load_dwordx4 v[92:95], v[72:73], off offset:64
	global_load_dwordx4 v[96:99], v[72:73], off
	v_lshlrev_b32_e32 v69, 2, v156
	v_and_b32_e32 v69, 12, v69
	v_bfe_u32 v72, v156, 2, 2
	v_bitop3_b32 v69, v69, v71, v72 bitop3:0x36
	v_lshl_add_u32 v159, v69, 4, 0
	v_lshlrev_b32_e32 v69, 2, v71
	v_and_b32_e32 v69, 12, v69
	v_bfe_u32 v72, v70, 2, 2
	v_bitop3_b32 v105, v69, v76, v72 bitop3:0x36
	v_lshlrev_b32_e32 v164, 4, v105
	v_or_b32_e32 v105, 4, v76
	v_lshlrev_b32_e32 v150, 2, v76
	v_bfe_u32 v74, v70, 1, 1
	v_and_b32_e32 v75, 12, v70
	v_bitop3_b32 v105, v69, v105, v72 bitop3:0x36
	v_lshlrev_b32_e32 v68, 3, v76
	v_or_b32_e32 v162, s6, v150
	v_lshrrev_b32_e32 v73, 2, v71
	v_or_b32_e32 v77, v76, v75
	v_bitop3_b32 v75, v76, v74, v75 bitop3:0x36
	v_cmp_eq_u32_e64 s[38:39], 0, v76
	v_lshlrev_b32_e32 v165, 4, v105
	v_or_b32_e32 v105, 8, v76
	v_or_b32_e32 v76, 12, v76
	v_or_b32_e32 v73, v162, v73
	s_add_i32 s1, 0, 0x10000
	v_lshlrev_b32_e32 v70, 3, v70
	v_bitop3_b32 v105, v69, v105, v72 bitop3:0x36
	v_bitop3_b32 v69, v69, v76, v72 bitop3:0x36
	v_lshl_add_u32 v75, v75, 4, s1
	v_and_b32_e32 v70, 8, v70
	v_lshlrev_b32_e32 v167, 4, v69
	v_readlane_b32 s2, v252, 8
	v_lshlrev_b32_e32 v69, 8, v73
	v_or_b32_e32 v158, s6, v71
	v_add_u32_e32 v78, v75, v70
	v_lshlrev_b32_e32 v166, 4, v105
	v_lshl_add_u32 v168, v71, 8, s2
	v_add_u32_e32 v71, v75, v69
	v_bitop3_b32 v72, v74, v77, 2 bitop3:0x36
	v_bitop3_b32 v75, v74, v77, 4 bitop3:0x36
	v_bitop3_b32 v105, v74, v77, 6 bitop3:0x36
	v_bitop3_b32 v107, v74, v77, 8 bitop3:0x36
	v_bitop3_b32 v109, v74, v77, 10 bitop3:0x36
	v_bitop3_b32 v111, v74, v77, 12 bitop3:0x36
	v_bitop3_b32 v74, v74, v77, 14 bitop3:0x36
	v_add_u32_e32 v79, s1, v70
	v_lshlrev_b32_e32 v72, 4, v72
	v_lshlrev_b32_e32 v75, 4, v75
	v_lshlrev_b32_e32 v105, 4, v105
	v_lshlrev_b32_e32 v107, 4, v107
	v_lshlrev_b32_e32 v109, 4, v109
	v_lshlrev_b32_e32 v111, 4, v111
	v_lshlrev_b32_e32 v74, 4, v74
	v_lshlrev_b32_e32 v163, 8, v156
	v_add_u32_e32 v80, 0x10000, v159
	v_add_u32_e32 v81, 0x12000, v159
	v_add_u32_e32 v82, 0x14000, v159
	v_add_u32_e32 v83, 0x16000, v159
	v_add_u32_e32 v100, 0x18000, v159
	v_add_u32_e32 v101, 0x1a000, v159
	v_add_u32_e32 v102, 0x1c000, v159
	v_add_u32_e32 v103, 0x1e000, v159
	v_add_u32_e32 v104, 0x20000, v159
	v_add_u32_e32 v73, v79, v72
	v_add3_u32 v72, s1, v72, v69
	v_add_u32_e32 v76, v79, v75
	v_add3_u32 v75, s1, v75, v69
	v_add_u32_e32 v106, v79, v105
	v_add3_u32 v105, s1, v105, v69
	v_add_u32_e32 v108, v79, v107
	v_add3_u32 v107, s1, v107, v69
	v_add_u32_e32 v110, v79, v109
	v_add3_u32 v109, s1, v109, v69
	v_add_u32_e32 v112, v79, v111
	v_add3_u32 v111, s1, v111, v69
	v_add_u32_e32 v77, v79, v74
	v_add3_u32 v74, s1, v74, v69
	v_lshl_add_u32 v160, v158, 8, 0
	v_add_u32_e32 v161, 0x80, v158
	v_mov_b32_e32 v151, v209
	s_add_i32 s17, s14, s15
	v_add_u32_e32 v169, v80, v163
	v_add_u32_e32 v170, v81, v163
	v_add_u32_e32 v171, v82, v163
	v_add_u32_e32 v172, v83, v163
	v_add_u32_e32 v173, v100, v163
	v_add_u32_e32 v174, v101, v163
	v_add_u32_e32 v175, v102, v163
	v_add_u32_e32 v176, v103, v163
	v_add_u32_e32 v177, v104, v163
	v_lshlrev_b32_e32 v208, 1, v68
	v_add_u32_e32 v178, v78, v69
	v_add_u32_e32 v179, v71, v70
	v_add_u32_e32 v180, v73, v69
	v_add_u32_e32 v181, v72, v70
	v_add_u32_e32 v182, v76, v69
	v_add_u32_e32 v183, v75, v70
	v_add_u32_e32 v184, v106, v69
	v_add_u32_e32 v185, v105, v70
	v_add_u32_e32 v186, v108, v69
	v_add_u32_e32 v187, v107, v70
	v_add_u32_e32 v188, v110, v69
	v_add_u32_e32 v189, v109, v70
	v_add_u32_e32 v190, v112, v69
	v_add_u32_e32 v191, v111, v70
	v_add_u32_e32 v192, v77, v69
	v_add_u32_e32 v193, v74, v70
	s_waitcnt vmcnt(0)
	s_branch .LBB0_723

; #define LAS __attribute__((address_space(3)))
; __device__ __forceinline__ void attn_phase(Frame& F, h16* Obr) {
;     ...
;     for (int I = i_lo; I < i_hi; I += i_st) {
;         const AttItem cu = nx;
;         __syncthreads();
;         {   const int ch = tid & 15, r4 = tid >> 4;
; #pragma unroll
;             for (int j = 0; j < 17; ++j) { const bool isv = j >= 8; const int rr = isv ? r4 + 32 * (j - 8) : r4 + 32 * j;
;                 if (j < 16 || tid < 256) *(LAS u32x4*)(lds + (isv ? ATT_V : ATT_K) + att_off(rr, ch)) = kv[j]; } }
.LBB0_723:
	s_waitcnt vmcnt(63) expcnt(7) lgkmcnt(15)
	s_barrier
	s_and_saveexec_b64 s[26:27], s[36:37]
	s_cbranch_execz .Lattn_v17
	s_add_u32 m0, s101, 0x10000
	s_nop 0
	global_load_lds_dwordx4 v[16:17], off offset:2048

; #define LAS __attribute__((address_space(3)))
; __device__ __forceinline__ void attn_phase(Frame& F, h16* Obr) {
;     ...
;         if (I + i_st < i_hi) { nx = att_decode(I + i_st); ATT_ISSUE(nx); }
;         const int idx0 = cu.idx0, L = cu.L;
;         const int qtok = cu.p + cu.r * (idx0 + 16 * w + q16);
;         f32x4 sc[9];
;         h16x8 kfb[2][4];
; #pragma unroll
;         for (int s = 0; s < 4; ++s) kfb[0][s] = *(const LAS h16x8*)(lds + ATT_K + att_off(16 * w + q16, 4 * s + g));
; #pragma unroll
;         for (int tt = 0; tt < 9; ++tt) {
;             if (tt + 1 < 9) {
; #pragma unroll
;                 for (int s = 0; s < 4; ++s) kfb[(tt + 1) & 1][s] = *(const LAS h16x8*)(lds + ATT_K + att_off(16 * (w + tt + 1) + q16, 4 * s + g)); }
;             asm volatile("" ::: "memory");
;             f32x4 a = {0.f, 0.f, 0.f, 0.f};
; #pragma unroll
;             for (int s = 0; s < 4; ++s) a = __builtin_amdgcn_mfma_f32_16x16x32_f16(kfb[tt & 1][s], Qf[s], a, 0, 0, 0);
;             sc[tt] = a; }
.LBB0_737:
	v_add_u32_e32 v100, s51, v158
	v_mul_lo_u32 v128, s0, v100
	v_add_u32_e32 v100, v160, v164
	ds_read_b128 v[100:103], v100
	v_add_u32_e32 v104, v160, v165
	ds_read_b128 v[104:107], v104
	v_add_u32_e32 v108, v160, v166
	ds_read_b128 v[108:111], v108
	v_add_u32_e32 v129, v168, v164
	ds_read_b128 v[116:119], v129 offset:4096
	v_add_u32_e32 v112, v160, v167
	s_waitcnt vmcnt(20) lgkmcnt(3)
	v_mfma_f32_16x16x32_f16 v[100:103], v[100:103], v[96:99], 0
	ds_read_b128 v[112:115], v112
	v_add_u32_e32 v146, v168, v165
	ds_read_b128 v[120:123], v146 offset:4096
	s_waitcnt lgkmcnt(4)
	v_mfma_f32_16x16x32_f16 v[100:103], v[104:107], v[92:95], v[100:103]
	s_add_u32 m0, s101, 0x0
	s_nop 0
	global_load_lds_dwordx4 v[36:37], off offset:2048
	v_add_u32_e32 v147, v168, v166
	ds_read_b128 v[124:127], v147 offset:4096
	v_add_u32_e32 v206, v168, v167
	s_waitcnt lgkmcnt(4)
	v_mfma_f32_16x16x32_f16 v[100:103], v[108:111], v[88:91], v[100:103]
	ds_read_b128 v[130:133], v206 offset:4096
	s_waitcnt lgkmcnt(4)
	v_mfma_f32_16x16x32_f16 v[104:107], v[116:119], v[96:99], 0
	s_waitcnt lgkmcnt(3)
	v_mfma_f32_16x16x32_f16 v[100:103], v[112:115], v[84:87], v[100:103]
	ds_read_b128 v[108:111], v129 offset:8192
	ds_read_b128 v[112:115], v146 offset:8192
	ds_read_b128 v[134:137], v147 offset:8192
	ds_read_b128 v[138:141], v206 offset:8192
	s_waitcnt lgkmcnt(6)
	v_mfma_f32_16x16x32_f16 v[104:107], v[120:123], v[92:95], v[104:107]
	s_add_u32 m0, s101, 0x2000
	s_nop 0
	global_load_lds_dwordx4 v[38:39], off offset:2048
	s_waitcnt lgkmcnt(3)
	v_mfma_f32_16x16x32_f16 v[108:111], v[108:111], v[96:99], 0
	v_mfma_f32_16x16x32_f16 v[104:107], v[124:127], v[88:91], v[104:107]
	s_waitcnt lgkmcnt(2)
	v_mfma_f32_16x16x32_f16 v[108:111], v[112:115], v[92:95], v[108:111]
	v_mfma_f32_16x16x32_f16 v[104:107], v[130:133], v[84:87], v[104:107]
	s_add_u32 m0, s101, 0x4000
	s_nop 0
	global_load_lds_dwordx4 v[44:45], off offset:2048
	ds_read_b128 v[116:119], v129 offset:12288
	ds_read_b128 v[120:123], v146 offset:12288
	ds_read_b128 v[124:127], v147 offset:12288
	ds_read_b128 v[130:133], v206 offset:12288
	s_waitcnt lgkmcnt(5)
	v_mfma_f32_16x16x32_f16 v[108:111], v[134:137], v[88:91], v[108:111]
	s_waitcnt lgkmcnt(3)
	v_mfma_f32_16x16x32_f16 v[112:115], v[116:119], v[96:99], 0
	v_mfma_f32_16x16x32_f16 v[108:111], v[138:141], v[84:87], v[108:111]
	ds_read_b128 v[134:137], v129 offset:16384
	ds_read_b128 v[138:141], v146 offset:16384
	ds_read_b128 v[142:145], v147 offset:16384
	ds_read_b128 v[152:155], v206 offset:16384
	s_waitcnt lgkmcnt(6)
	v_mfma_f32_16x16x32_f16 v[112:115], v[120:123], v[92:95], v[112:115]
	s_add_u32 m0, s101, 0x6000
	s_nop 0
	global_load_lds_dwordx4 v[46:47], off offset:2048
	s_waitcnt lgkmcnt(3)
	v_mfma_f32_16x16x32_f16 v[116:119], v[134:137], v[96:99], 0
	v_mfma_f32_16x16x32_f16 v[112:115], v[124:127], v[88:91], v[112:115]
	s_waitcnt lgkmcnt(2)
	v_mfma_f32_16x16x32_f16 v[116:119], v[138:141], v[92:95], v[116:119]
	v_mfma_f32_16x16x32_f16 v[112:115], v[130:133], v[84:87], v[112:115]
	s_add_u32 m0, s101, 0x8000
	s_nop 0
	global_load_lds_dwordx4 v[52:53], off offset:2048
	ds_read_b128 v[120:123], v129 offset:20480
	ds_read_b128 v[124:127], v146 offset:20480
	ds_read_b128 v[130:133], v147 offset:20480
	ds_read_b128 v[194:197], v206 offset:20480
	s_waitcnt lgkmcnt(5)
	v_mfma_f32_16x16x32_f16 v[116:119], v[142:145], v[88:91], v[116:119]
	s_waitcnt lgkmcnt(3)
	v_mfma_f32_16x16x32_f16 v[120:123], v[120:123], v[96:99], 0
	v_mfma_f32_16x16x32_f16 v[116:119], v[152:155], v[84:87], v[116:119]
	ds_read_b128 v[134:137], v129 offset:24576
	ds_read_b128 v[138:141], v146 offset:24576
	ds_read_b128 v[142:145], v147 offset:24576
	ds_read_b128 v[152:155], v206 offset:24576
	s_waitcnt lgkmcnt(6)
	v_mfma_f32_16x16x32_f16 v[120:123], v[124:127], v[92:95], v[120:123]
	s_add_u32 m0, s101, 0xa000
	s_nop 0
	global_load_lds_dwordx4 v[54:55], off offset:2048
	s_waitcnt lgkmcnt(3)
	v_mfma_f32_16x16x32_f16 v[124:127], v[134:137], v[96:99], 0
	s_waitcnt lgkmcnt(2)
	v_mfma_f32_16x16x32_f16 v[124:127], v[138:141], v[92:95], v[124:127]
	v_mfma_f32_16x16x32_f16 v[120:123], v[130:133], v[88:91], v[120:123]
	s_waitcnt lgkmcnt(1)
	v_mfma_f32_16x16x32_f16 v[124:127], v[142:145], v[88:91], v[124:127]
	s_add_u32 m0, s101, 0xc000
	s_nop 0
	global_load_lds_dwordx4 v[60:61], off offset:2048
	v_mfma_f32_16x16x32_f16 v[120:123], v[194:197], v[84:87], v[120:123]
	ds_read_b128 v[130:133], v129 offset:28672
	ds_read_b128 v[194:197], v146 offset:28672
	ds_read_b128 v[198:201], v147 offset:28672
	ds_read_b128 v[202:205], v206 offset:28672
	s_waitcnt lgkmcnt(4)
	v_mfma_f32_16x16x32_f16 v[124:127], v[152:155], v[84:87], v[124:127]
	ds_read_b128 v[134:137], v129 offset:32768
	ds_read_b128 v[138:141], v146 offset:32768
	ds_read_b128 v[142:145], v147 offset:32768
	ds_read_b128 v[152:155], v206 offset:32768
	s_waitcnt lgkmcnt(7)
	v_mfma_f32_16x16x32_f16 v[130:133], v[130:133], v[96:99], 0
	s_waitcnt lgkmcnt(3)
	v_mfma_f32_16x16x32_f16 v[96:99], v[134:137], v[96:99], 0
	s_add_u32 m0, s101, 0xe000
	s_nop 0
	global_load_lds_dwordx4 v[62:63], off offset:2048
	v_mfma_f32_16x16x32_f16 v[130:133], v[194:197], v[92:95], v[130:133]
	s_waitcnt lgkmcnt(2)
	v_mfma_f32_16x16x32_f16 v[92:95], v[138:141], v[92:95], v[96:99]
	v_mfma_f32_16x16x32_f16 v[130:133], v[198:201], v[88:91], v[130:133]
	s_waitcnt lgkmcnt(1)
	v_mfma_f32_16x16x32_f16 v[88:91], v[142:145], v[88:91], v[92:95]
	v_mfma_f32_16x16x32_f16 v[130:133], v[202:205], v[84:87], v[130:133]
	s_waitcnt lgkmcnt(0)
	v_mfma_f32_16x16x32_f16 v[84:87], v[152:155], v[84:87], v[88:91]
	s_cmp_ge_i32 s17, s16
	s_waitcnt vmcnt(0) lgkmcnt(0)
	s_barrier
	s_cbranch_scc1 .LBB0_731
	s_mul_hi_i32 s1, s17, 0x2aaaaaab
	s_lshr_b32 s2, s1, 31
	s_ashr_i32 s1, s1, 3
	s_add_i32 s1, s1, s2
	s_mul_i32 s2, s1, 0xffffffd0
	s_add_i32 s2, s17, s2
	s_cmp_lt_i32 s2, 16
	s_cbranch_scc1 .LBB0_732
	s_cmp_gt_u32 s2, 31
	s_mov_b64 s[26:27], -1
	s_cbranch_scc0 .LBB0_729
	s_sub_i32 s19, s2, 32
	s_mov_b64 s[26:27], 0

.LBB0_734:
	s_ashr_i32 s4, s1, 3
	s_and_b32 s46, s1, 7
	s_ff1_i32_b32 s1, s45
	s_lshr_b32 s47, 0x800, s1
	s_lshl_b32 s48, s2, 7
	v_add_u32_e32 v70, s48, v157
	s_add_i32 s1, s47, -1
	s_ashr_i32 s5, s4, 31
	s_lshl_b64 s[26:27], s[4:5], 11
	s_lshl_b32 s2, s46, 8
	s_add_u32 s40, s26, s19
	s_addc_u32 s41, s27, 0
	s_mul_i32 s4, s40, 0x1800
	s_add_u32 s2, s4, s2
	s_add_u32 s2, s2, 0x800
	v_lshl_add_u64 v[68:69], v[148:149], 0, s[2:3]
	s_mul_i32 s5, s45, 0x1800
	v_mov_b32_e32 v1, 0
	v_mov_b32_e32 v9, 0
	v_mov_b32_e32 v21, 0
	v_mov_b32_e32 v29, 0
	v_med3_i32 v0, v70, 0, s1
	v_mul_u32_u24_e32 v0, s5, v0
	v_lshl_add_u64 v[36:37], v[0:1], 0, v[68:69]
	s_add_u32 m0, s100, 0x0
	s_nop 0
	global_load_lds_dwordx4 v[36:37], off
	v_add_u32_e32 v8, 0x20, v70
	v_med3_i32 v8, v8, 0, s1
	v_mul_u32_u24_e32 v8, s5, v8
	v_lshl_add_u64 v[38:39], v[8:9], 0, v[68:69]
	s_add_u32 m0, s100, 0x2000
	s_nop 0
	global_load_lds_dwordx4 v[38:39], off
	v_add_u32_e32 v20, 0x40, v70
	v_med3_i32 v20, v20, 0, s1
	v_mul_u32_u24_e32 v20, s5, v20
	v_lshl_add_u64 v[44:45], v[20:21], 0, v[68:69]
	s_add_u32 m0, s100, 0x4000
	s_nop 0
	global_load_lds_dwordx4 v[44:45], off
	v_add_u32_e32 v28, 0x60, v70
	v_med3_i32 v28, v28, 0, s1
	v_mul_u32_u24_e32 v28, s5, v28
	v_lshl_add_u64 v[46:47], v[28:29], 0, v[68:69]
	s_add_u32 m0, s100, 0x6000
	s_nop 0
	global_load_lds_dwordx4 v[46:47], off
	v_add_u32_e32 v0, 0x80, v70
	v_med3_i32 v0, v0, 0, s1
	v_mul_u32_u24_e32 v0, s5, v0
	v_lshl_add_u64 v[52:53], v[0:1], 0, v[68:69]
	s_add_u32 m0, s100, 0x8000
	s_nop 0
	global_load_lds_dwordx4 v[52:53], off
	v_add_u32_e32 v8, 0xa0, v70
	v_med3_i32 v8, v8, 0, s1
	v_mul_u32_u24_e32 v8, s5, v8
	v_lshl_add_u64 v[54:55], v[8:9], 0, v[68:69]
	s_add_u32 m0, s100, 0xa000
	s_nop 0
	global_load_lds_dwordx4 v[54:55], off
	v_add_u32_e32 v20, 0xc0, v70
	v_med3_i32 v20, v20, 0, s1
	v_mul_u32_u24_e32 v20, s5, v20
	v_lshl_add_u64 v[60:61], v[20:21], 0, v[68:69]
	s_add_u32 m0, s100, 0xc000
	s_nop 0
	global_load_lds_dwordx4 v[60:61], off
	v_add_u32_e32 v28, 0xe0, v70
	v_med3_i32 v28, v28, 0, s1
	v_mul_u32_u24_e32 v28, s5, v28
	v_lshl_add_u64 v[62:63], v[28:29], 0, v[68:69]
	s_add_u32 m0, s100, 0xe000
	s_nop 0
	global_load_lds_dwordx4 v[62:63], off
	v_add_u32_e32 v0, 0x100, v70
	v_med3_i32 v0, v0, 0, s1
	v_mul_u32_u24_e32 v0, s5, v0
	v_lshl_add_u64 v[16:17], v[0:1], 0, v[68:69]
	v_add_u32_e32 v68, s48, v158
	v_mul_lo_u32 v68, v68, s45
	v_add_u32_e32 v68, s19, v68
	v_readlane_b32 s4, v252, 3
	v_ashrrev_i32_e32 v69, 31, v68
	v_readlane_b32 s5, v252, 4
	v_lshl_add_u64 v[68:69], s[26:27], 0, v[68:69]
	s_lshl_b32 s1, s46, 7
	v_mov_b64_e32 v[70:71], s[4:5]
	v_mad_u64_u32 v[70:71], s[4:5], v68, s35, v[70:71]
	v_mad_i32_i24 v71, v69, s35, v71
	s_lshl_b32 s2, s1, 1
	v_lshl_add_u64 v[68:69], v[70:71], 0, s[2:3]
	v_lshl_add_u64 v[80:81], v[68:69], 0, v[208:209]
	global_load_dwordx4 v[68:71], v[80:81], off
	global_load_dwordx4 v[72:75], v[80:81], off offset:64
	global_load_dwordx4 v[76:79], v[80:81], off offset:128
	s_nop 0
	global_load_dwordx4 v[80:83], v[80:81], off offset:192
